# code placement: the four GEMM K-loop heads aligned to 64 bytes (.p2align 6), on top of the 0-mod-8 pads
# baseline (speedup 1.0000x reference)
; template <class Epi>
; __device__ __forceinline__ void gemm_phase(LAS unsigned char* lds, const Gemm g, const StaticOrder& S, const Epi& E) {
;     ...
;         const char* nA = has_next ? (const char*)g.A + (size_t)npm * tstep + (size_t)nk0 * kstep : cA; const char* nB = has_next ? (const char*)g.Bt + (size_t)npn * tstep + (size_t)nk0 * kstep : cB;
;         const int nt = cnk;
;         for (int t = 0; t < nt; t += 2) {
;             const bool last = (t == nt - 2);
;             const char* a1 = cA + (size_t)(t + 1) * kstep;
;             const char* a2 = last ? nA : cA + (size_t)(t + 2) * kstep; const char* b2 = last ? nB : cB + (size_t)(t + 2) * kstep;
;             const char* a3 = a2 + kstep; const char* b3 = b2 + kstep;
;     ...
; #pragma unroll
;         for (int a = 0; a < 2; ++a)
; #pragma unroll
;             for (int b = 0; b < 2; ++b)
; #pragma unroll
;                 for (int m = 0; m < 4; ++m)
; #pragma unroll
;                     for (int n = 0; n < 2; ++n) acc[a][b][m][n] = (f32x4){0.f, 0.f, 0.f, 0.f};
.LBB0_566:
	s_ashr_i32 s61, s60, 31
	s_lshl_b64 s[30:31], s[60:61], 19
	s_add_u32 s66, s1, s30
	s_addc_u32 s67, s0, s31
	s_ashr_i32 s63, s62, 31
	s_lshl_b64 s[30:31], s[62:63], 19
	s_add_u32 s68, s4, s30
	s_addc_u32 s69, s3, s31
	s_cmp_eq_u32 s29, 0
	s_cbranch_scc1 .LBB0_569
	s_and_b64 s[30:31], s[70:71], exec
	s_cselect_b32 s33, s67, s51
	s_cselect_b32 s38, s66, s50
	s_cselect_b32 s39, s69, s53
	s_cselect_b32 s61, s68, s52
	s_add_i32 s63, s29, -2
	s_add_u32 s72, s52, 0x100
	s_addc_u32 s73, s53, 0
	s_add_u32 s50, s50, 0x40080
	v_mov_b32_e32 v8, 0
	s_addc_u32 s51, s51, 0
	s_mov_b32 s52, 0
	v_mov_b32_e32 v9, v8
	v_mov_b32_e32 v10, v8
	v_mov_b32_e32 v11, v8
	v_mov_b32_e32 v12, v8
	v_mov_b32_e32 v13, v8
	v_mov_b32_e32 v14, v8
	v_mov_b32_e32 v15, v8
	v_mov_b32_e32 v24, v8
	v_mov_b32_e32 v25, v8
	v_mov_b32_e32 v26, v8
	v_mov_b32_e32 v27, v8
	v_mov_b32_e32 v28, v8
	v_mov_b32_e32 v29, v8
	v_mov_b32_e32 v30, v8
	v_mov_b32_e32 v31, v8
	v_mov_b32_e32 v40, v8
	v_mov_b32_e32 v41, v8
	v_mov_b32_e32 v42, v8
	v_mov_b32_e32 v43, v8
	v_mov_b32_e32 v44, v8
	v_mov_b32_e32 v45, v8
	v_mov_b32_e32 v46, v8
	v_mov_b32_e32 v47, v8
	v_mov_b32_e32 v56, v8
	v_mov_b32_e32 v57, v8
	v_mov_b32_e32 v58, v8
	v_mov_b32_e32 v59, v8
	v_mov_b32_e32 v60, v8
	v_mov_b32_e32 v61, v8
	v_mov_b32_e32 v62, v8
	v_mov_b32_e32 v63, v8
	v_mov_b32_e32 v16, v8
	v_mov_b32_e32 v17, v8
	v_mov_b32_e32 v18, v8
	v_mov_b32_e32 v19, v8
	v_mov_b32_e32 v20, v8
	v_mov_b32_e32 v21, v8
	v_mov_b32_e32 v22, v8
	v_mov_b32_e32 v23, v8
	v_mov_b32_e32 v32, v8
	v_mov_b32_e32 v33, v8
	v_mov_b32_e32 v34, v8
	v_mov_b32_e32 v35, v8
	v_mov_b32_e32 v36, v8
	v_mov_b32_e32 v37, v8
	v_mov_b32_e32 v38, v8
	v_mov_b32_e32 v39, v8
	v_mov_b32_e32 v48, v8
	v_mov_b32_e32 v49, v8
	v_mov_b32_e32 v50, v8
	v_mov_b32_e32 v51, v8
	v_mov_b32_e32 v52, v8
	v_mov_b32_e32 v53, v8
	v_mov_b32_e32 v54, v8
	v_mov_b32_e32 v55, v8
	v_mov_b32_e32 v64, v8
	v_mov_b32_e32 v65, v8
	v_mov_b32_e32 v66, v8
	v_mov_b32_e32 v67, v8
	v_mov_b32_e32 v68, v8
	v_mov_b32_e32 v69, v8
	v_mov_b32_e32 v70, v8
	v_mov_b32_e32 v71, v8
	v_mov_b32_e32 v72, v8
	v_mov_b32_e32 v73, v8
	v_mov_b32_e32 v74, v8
	v_mov_b32_e32 v75, v8
	v_mov_b32_e32 v76, v8
	v_mov_b32_e32 v77, v8
	v_mov_b32_e32 v78, v8
	v_mov_b32_e32 v79, v8
	v_mov_b32_e32 v88, v8
	v_mov_b32_e32 v89, v8
	v_mov_b32_e32 v90, v8
	v_mov_b32_e32 v91, v8
	v_mov_b32_e32 v92, v8
	v_mov_b32_e32 v93, v8
	v_mov_b32_e32 v94, v8
	v_mov_b32_e32 v95, v8
	v_mov_b32_e32 v104, v8
	v_mov_b32_e32 v105, v8
	v_mov_b32_e32 v106, v8
	v_mov_b32_e32 v107, v8
	v_mov_b32_e32 v108, v8
	v_mov_b32_e32 v109, v8
	v_mov_b32_e32 v110, v8
	v_mov_b32_e32 v111, v8
	v_mov_b32_e32 v120, v8
	v_mov_b32_e32 v121, v8
	v_mov_b32_e32 v122, v8
	v_mov_b32_e32 v123, v8
	v_mov_b32_e32 v124, v8
	v_mov_b32_e32 v125, v8
	v_mov_b32_e32 v126, v8
	v_mov_b32_e32 v127, v8
	v_mov_b32_e32 v80, v8
	v_mov_b32_e32 v81, v8
	v_mov_b32_e32 v82, v8
	v_mov_b32_e32 v83, v8
	v_mov_b32_e32 v84, v8
	v_mov_b32_e32 v85, v8
	v_mov_b32_e32 v86, v8
	v_mov_b32_e32 v87, v8
	v_mov_b32_e32 v96, v8
	v_mov_b32_e32 v97, v8
	v_mov_b32_e32 v98, v8
	v_mov_b32_e32 v99, v8
	v_mov_b32_e32 v100, v8
	v_mov_b32_e32 v101, v8
	v_mov_b32_e32 v102, v8
	v_mov_b32_e32 v103, v8
	v_mov_b32_e32 v112, v8
	v_mov_b32_e32 v113, v8
	v_mov_b32_e32 v114, v8
	v_mov_b32_e32 v115, v8
	v_mov_b32_e32 v116, v8
	v_mov_b32_e32 v117, v8
	v_mov_b32_e32 v118, v8
	v_mov_b32_e32 v119, v8
	v_mov_b32_e32 v128, v8
	v_mov_b32_e32 v129, v8
	v_mov_b32_e32 v130, v8
	v_mov_b32_e32 v131, v8
	v_mov_b32_e32 v132, v8
	v_mov_b32_e32 v133, v8
	v_mov_b32_e32 v134, v8
	v_mov_b32_e32 v135, v8
	.p2align	6

; template <class Epi>
; __device__ __forceinline__ void gemm_phase(LAS unsigned char* lds, const Gemm g, const StaticOrder& S, const Epi& E) {
;     ...
;         const char* nA = has_next ? (const char*)g.A + (size_t)npm * tstep + (size_t)nk0 * kstep : cA; const char* nB = has_next ? (const char*)g.Bt + (size_t)npn * tstep + (size_t)nk0 * kstep : cB;
;         const int nt = cnk;
;         for (int t = 0; t < nt; t += 2) {
;             const bool last = (t == nt - 2);
;             const char* a1 = cA + (size_t)(t + 1) * kstep;
;             const char* a2 = last ? nA : cA + (size_t)(t + 2) * kstep; const char* b2 = last ? nB : cB + (size_t)(t + 2) * kstep;
;             const char* a3 = a2 + kstep; const char* b3 = b2 + kstep;
;     ...
; #pragma unroll
;         for (int a = 0; a < 2; ++a)
; #pragma unroll
;             for (int b = 0; b < 2; ++b)
; #pragma unroll
;                 for (int m = 0; m < 4; ++m)
; #pragma unroll
;                     for (int n = 0; n < 2; ++n) acc[a][b][m][n] = (f32x4){0.f, 0.f, 0.f, 0.f};
.LBB0_1487:
	s_ashr_i32 s49, s48, 31
	s_lshl_b64 s[30:31], s[48:49], 19
	s_add_u32 s49, s53, s30
	s_addc_u32 s61, s52, s31
	s_lshl_b64 s[30:31], s[6:7], 7
	s_add_u32 s62, s49, s30
	s_addc_u32 s63, s61, s31
	s_ashr_i32 s61, s60, 31
	s_lshl_b64 s[64:65], s[60:61], 19
	s_add_u32 s49, s39, s64
	s_addc_u32 s61, s38, s65
	s_add_u32 s64, s49, s30
	s_addc_u32 s65, s61, s31
	s_cmp_lt_i32 s90, 1
	s_cbranch_scc1 .LBB0_1491
	s_and_b64 s[30:31], s[70:71], exec
	s_cselect_b32 s49, s63, s73
	s_cselect_b32 s61, s62, s72
	s_cselect_b32 s67, s65, s75
	s_cselect_b32 s69, s64, s74
	s_add_i32 s91, s90, -2
	s_mov_b64 s[50:51], s[96:97]
	s_add_u32 s96, s74, 0x100
	v_mov_b32_e32 v8, 0
	s_addc_u32 s97, s75, 0
	s_mov_b32 s94, 0
	v_mov_b32_e32 v9, v8
	v_mov_b32_e32 v10, v8
	v_mov_b32_e32 v11, v8
	v_mov_b32_e32 v12, v8
	v_mov_b32_e32 v13, v8
	v_mov_b32_e32 v14, v8
	v_mov_b32_e32 v15, v8
	v_mov_b32_e32 v24, v8
	v_mov_b32_e32 v25, v8
	v_mov_b32_e32 v26, v8
	v_mov_b32_e32 v27, v8
	v_mov_b32_e32 v28, v8
	v_mov_b32_e32 v29, v8
	v_mov_b32_e32 v30, v8
	v_mov_b32_e32 v31, v8
	v_mov_b32_e32 v40, v8
	v_mov_b32_e32 v41, v8
	v_mov_b32_e32 v42, v8
	v_mov_b32_e32 v43, v8
	v_mov_b32_e32 v44, v8
	v_mov_b32_e32 v45, v8
	v_mov_b32_e32 v46, v8
	v_mov_b32_e32 v47, v8
	v_mov_b32_e32 v56, v8
	v_mov_b32_e32 v57, v8
	v_mov_b32_e32 v58, v8
	v_mov_b32_e32 v59, v8
	v_mov_b32_e32 v60, v8
	v_mov_b32_e32 v61, v8
	v_mov_b32_e32 v62, v8
	v_mov_b32_e32 v63, v8
	v_mov_b32_e32 v16, v8
	v_mov_b32_e32 v17, v8
	v_mov_b32_e32 v18, v8
	v_mov_b32_e32 v19, v8
	v_mov_b32_e32 v20, v8
	v_mov_b32_e32 v21, v8
	v_mov_b32_e32 v22, v8
	v_mov_b32_e32 v23, v8
	v_mov_b32_e32 v32, v8
	v_mov_b32_e32 v33, v8
	v_mov_b32_e32 v34, v8
	v_mov_b32_e32 v35, v8
	v_mov_b32_e32 v36, v8
	v_mov_b32_e32 v37, v8
	v_mov_b32_e32 v38, v8
	v_mov_b32_e32 v39, v8
	v_mov_b32_e32 v48, v8
	v_mov_b32_e32 v49, v8
	v_mov_b32_e32 v50, v8
	v_mov_b32_e32 v51, v8
	v_mov_b32_e32 v52, v8
	v_mov_b32_e32 v53, v8
	v_mov_b32_e32 v54, v8
	v_mov_b32_e32 v55, v8
	v_mov_b32_e32 v64, v8
	v_mov_b32_e32 v65, v8
	v_mov_b32_e32 v66, v8
	v_mov_b32_e32 v67, v8
	v_mov_b32_e32 v68, v8
	v_mov_b32_e32 v69, v8
	v_mov_b32_e32 v70, v8
	v_mov_b32_e32 v71, v8
	v_mov_b32_e32 v72, v8
	v_mov_b32_e32 v73, v8
	v_mov_b32_e32 v74, v8
	v_mov_b32_e32 v75, v8
	v_mov_b32_e32 v76, v8
	v_mov_b32_e32 v77, v8
	v_mov_b32_e32 v78, v8
	v_mov_b32_e32 v79, v8
	v_mov_b32_e32 v88, v8
	v_mov_b32_e32 v89, v8
	v_mov_b32_e32 v90, v8
	v_mov_b32_e32 v91, v8
	v_mov_b32_e32 v92, v8
	v_mov_b32_e32 v93, v8
	v_mov_b32_e32 v94, v8
	v_mov_b32_e32 v95, v8
	v_mov_b32_e32 v104, v8
	v_mov_b32_e32 v105, v8
	v_mov_b32_e32 v106, v8
	v_mov_b32_e32 v107, v8
	v_mov_b32_e32 v108, v8
	v_mov_b32_e32 v109, v8
	v_mov_b32_e32 v110, v8
	v_mov_b32_e32 v111, v8
	v_mov_b32_e32 v120, v8
	v_mov_b32_e32 v121, v8
	v_mov_b32_e32 v122, v8
	v_mov_b32_e32 v123, v8
	v_mov_b32_e32 v124, v8
	v_mov_b32_e32 v125, v8
	v_mov_b32_e32 v126, v8
	v_mov_b32_e32 v127, v8
	v_mov_b32_e32 v80, v8
	v_mov_b32_e32 v81, v8
	v_mov_b32_e32 v82, v8
	v_mov_b32_e32 v83, v8
	v_mov_b32_e32 v84, v8
	v_mov_b32_e32 v85, v8
	v_mov_b32_e32 v86, v8
	v_mov_b32_e32 v87, v8
	v_mov_b32_e32 v96, v8
	v_mov_b32_e32 v97, v8
	v_mov_b32_e32 v98, v8
	v_mov_b32_e32 v99, v8
	v_mov_b32_e32 v100, v8
	v_mov_b32_e32 v101, v8
	v_mov_b32_e32 v102, v8
	v_mov_b32_e32 v103, v8
	v_mov_b32_e32 v112, v8
	v_mov_b32_e32 v113, v8
	v_mov_b32_e32 v114, v8
	v_mov_b32_e32 v115, v8
	v_mov_b32_e32 v116, v8
	v_mov_b32_e32 v117, v8
	v_mov_b32_e32 v118, v8
	v_mov_b32_e32 v119, v8
	v_mov_b32_e32 v128, v8
	v_mov_b32_e32 v129, v8
	v_mov_b32_e32 v130, v8
	v_mov_b32_e32 v131, v8
	v_mov_b32_e32 v132, v8
	v_mov_b32_e32 v133, v8
	v_mov_b32_e32 v134, v8
	v_mov_b32_e32 v135, v8
	.p2align	6

; template <class Epi>
; __device__ __forceinline__ void gemm_phase(LAS unsigned char* lds, const Gemm g, const StaticOrder& S, const Epi& E) {
;     ...
;         const char* nA = has_next ? (const char*)g.A + (size_t)npm * tstep + (size_t)nk0 * kstep : cA; const char* nB = has_next ? (const char*)g.Bt + (size_t)npn * tstep + (size_t)nk0 * kstep : cB;
;         const int nt = cnk;
;         for (int t = 0; t < nt; t += 2) {
;             const bool last = (t == nt - 2);
;             const char* a1 = cA + (size_t)(t + 1) * kstep;
;             const char* a2 = last ? nA : cA + (size_t)(t + 2) * kstep; const char* b2 = last ? nB : cB + (size_t)(t + 2) * kstep;
;             const char* a3 = a2 + kstep; const char* b3 = b2 + kstep;
;     ...
; #pragma unroll
;         for (int a = 0; a < 2; ++a)
; #pragma unroll
;             for (int b = 0; b < 2; ++b)
; #pragma unroll
;                 for (int m = 0; m < 4; ++m)
; #pragma unroll
;                     for (int n = 0; n < 2; ++n) acc[a][b][m][n] = (f32x4){0.f, 0.f, 0.f, 0.f};
.LBB0_1764:
	s_ashr_i32 s45, s44, 31
	s_lshl_b64 s[4:5], s[44:45], 19
	s_add_u32 s48, s53, s4
	s_addc_u32 s49, s52, s5
	s_ashr_i32 s47, s46, 31
	s_lshl_b64 s[4:5], s[46:47], 19
	s_add_u32 s54, s64, s4
	s_addc_u32 s55, s28, s5
	s_cmp_eq_u32 s1, 0
	s_cbranch_scc1 .LBB0_1760
	s_and_b64 s[4:5], s[62:63], exec
	s_cselect_b32 s4, s49, s59
	s_cselect_b32 s5, s48, s58
	s_cselect_b32 s21, s55, s61
	s_cselect_b32 s22, s54, s60
	s_add_i32 s23, s1, -2
	s_add_u32 s24, s60, 0x100
	s_addc_u32 s25, s61, 0
	s_add_u32 s58, s58, 0x40080
	v_mov_b32_e32 v8, 0
	s_addc_u32 s59, s59, 0
	s_mov_b32 s29, 0
	v_mov_b32_e32 v9, v8
	v_mov_b32_e32 v10, v8
	v_mov_b32_e32 v11, v8
	v_mov_b32_e32 v16, v8
	v_mov_b32_e32 v17, v8
	v_mov_b32_e32 v18, v8
	v_mov_b32_e32 v19, v8
	v_mov_b32_e32 v24, v8
	v_mov_b32_e32 v25, v8
	v_mov_b32_e32 v26, v8
	v_mov_b32_e32 v27, v8
	v_mov_b32_e32 v32, v8
	v_mov_b32_e32 v33, v8
	v_mov_b32_e32 v34, v8
	v_mov_b32_e32 v35, v8
	v_mov_b32_e32 v40, v8
	v_mov_b32_e32 v41, v8
	v_mov_b32_e32 v42, v8
	v_mov_b32_e32 v43, v8
	v_mov_b32_e32 v48, v8
	v_mov_b32_e32 v49, v8
	v_mov_b32_e32 v50, v8
	v_mov_b32_e32 v51, v8
	v_mov_b32_e32 v56, v8
	v_mov_b32_e32 v57, v8
	v_mov_b32_e32 v58, v8
	v_mov_b32_e32 v59, v8
	v_mov_b32_e32 v64, v8
	v_mov_b32_e32 v65, v8
	v_mov_b32_e32 v66, v8
	v_mov_b32_e32 v67, v8
	v_mov_b32_e32 v12, v8
	v_mov_b32_e32 v13, v8
	v_mov_b32_e32 v14, v8
	v_mov_b32_e32 v15, v8
	v_mov_b32_e32 v20, v8
	v_mov_b32_e32 v21, v8
	v_mov_b32_e32 v22, v8
	v_mov_b32_e32 v23, v8
	v_mov_b32_e32 v28, v8
	v_mov_b32_e32 v29, v8
	v_mov_b32_e32 v30, v8
	v_mov_b32_e32 v31, v8
	v_mov_b32_e32 v36, v8
	v_mov_b32_e32 v37, v8
	v_mov_b32_e32 v38, v8
	v_mov_b32_e32 v39, v8
	v_mov_b32_e32 v44, v8
	v_mov_b32_e32 v45, v8
	v_mov_b32_e32 v46, v8
	v_mov_b32_e32 v47, v8
	v_mov_b32_e32 v52, v8
	v_mov_b32_e32 v53, v8
	v_mov_b32_e32 v54, v8
	v_mov_b32_e32 v55, v8
	v_mov_b32_e32 v60, v8
	v_mov_b32_e32 v61, v8
	v_mov_b32_e32 v62, v8
	v_mov_b32_e32 v63, v8
	v_mov_b32_e32 v68, v8
	v_mov_b32_e32 v69, v8
	v_mov_b32_e32 v70, v8
	v_mov_b32_e32 v71, v8
	v_mov_b32_e32 v72, v8
	v_mov_b32_e32 v73, v8
	v_mov_b32_e32 v74, v8
	v_mov_b32_e32 v75, v8
	v_mov_b32_e32 v80, v8
	v_mov_b32_e32 v81, v8
	v_mov_b32_e32 v82, v8
	v_mov_b32_e32 v83, v8
	v_mov_b32_e32 v88, v8
	v_mov_b32_e32 v89, v8
	v_mov_b32_e32 v90, v8
	v_mov_b32_e32 v91, v8
	v_mov_b32_e32 v96, v8
	v_mov_b32_e32 v97, v8
	v_mov_b32_e32 v98, v8
	v_mov_b32_e32 v99, v8
	v_mov_b32_e32 v104, v8
	v_mov_b32_e32 v105, v8
	v_mov_b32_e32 v106, v8
	v_mov_b32_e32 v107, v8
	v_mov_b32_e32 v112, v8
	v_mov_b32_e32 v113, v8
	v_mov_b32_e32 v114, v8
	v_mov_b32_e32 v115, v8
	v_mov_b32_e32 v120, v8
	v_mov_b32_e32 v121, v8
	v_mov_b32_e32 v122, v8
	v_mov_b32_e32 v123, v8
	v_mov_b32_e32 v128, v8
	v_mov_b32_e32 v129, v8
	v_mov_b32_e32 v130, v8
	v_mov_b32_e32 v131, v8
	v_mov_b32_e32 v76, v8
	v_mov_b32_e32 v77, v8
	v_mov_b32_e32 v78, v8
	v_mov_b32_e32 v79, v8
	v_mov_b32_e32 v84, v8
	v_mov_b32_e32 v85, v8
	v_mov_b32_e32 v86, v8
	v_mov_b32_e32 v87, v8
	v_mov_b32_e32 v92, v8
	v_mov_b32_e32 v93, v8
	v_mov_b32_e32 v94, v8
	v_mov_b32_e32 v95, v8
	v_mov_b32_e32 v100, v8
	v_mov_b32_e32 v101, v8
	v_mov_b32_e32 v102, v8
	v_mov_b32_e32 v103, v8
	v_mov_b32_e32 v108, v8
	v_mov_b32_e32 v109, v8
	v_mov_b32_e32 v110, v8
	v_mov_b32_e32 v111, v8
	v_mov_b32_e32 v116, v8
	v_mov_b32_e32 v117, v8
	v_mov_b32_e32 v118, v8
	v_mov_b32_e32 v119, v8
	v_mov_b32_e32 v124, v8
	v_mov_b32_e32 v125, v8
	v_mov_b32_e32 v126, v8
	v_mov_b32_e32 v127, v8
	v_mov_b32_e32 v132, v8
	v_mov_b32_e32 v133, v8
	v_mov_b32_e32 v134, v8
	v_mov_b32_e32 v135, v8
	.p2align	6

; template <class Epi>
; __device__ __forceinline__ void gemm_phase(LAS unsigned char* lds, const Gemm g, const StaticOrder& S, const Epi& E) {
;     ...
;         for (int t = 0; t < nt; t += 2) {
;             const bool last = (t == nt - 2);
;             const char* a1 = cA + (size_t)(t + 1) * kstep;
;             const char* a2 = last ? nA : cA + (size_t)(t + 2) * kstep; const char* b2 = last ? nB : cB + (size_t)(t + 2) * kstep;
;     ...
; #pragma unroll
;         for (int a = 0; a < 2; ++a)
; #pragma unroll
;             for (int b = 0; b < 2; ++b)
; #pragma unroll
;                 for (int m = 0; m < 4; ++m)
; #pragma unroll
;                     for (int n = 0; n < 2; ++n) acc[a][b][m][n] = (f32x4){0.f, 0.f, 0.f, 0.f};
.LBB0_1858:
	s_add_i32 s74, s73, -2
	s_add_u32 s75, s58, 0x100
	v_mov_b32_e32 v8, 0
	s_addc_u32 s78, s59, 0
	s_mov_b32 s60, 0
	v_mov_b32_e32 v9, v8
	v_mov_b32_e32 v10, v8
	v_mov_b32_e32 v11, v8
	v_mov_b32_e32 v12, v8
	v_mov_b32_e32 v13, v8
	v_mov_b32_e32 v14, v8
	v_mov_b32_e32 v15, v8
	v_mov_b32_e32 v24, v8
	v_mov_b32_e32 v25, v8
	v_mov_b32_e32 v26, v8
	v_mov_b32_e32 v27, v8
	v_mov_b32_e32 v28, v8
	v_mov_b32_e32 v29, v8
	v_mov_b32_e32 v30, v8
	v_mov_b32_e32 v31, v8
	v_mov_b32_e32 v40, v8
	v_mov_b32_e32 v41, v8
	v_mov_b32_e32 v42, v8
	v_mov_b32_e32 v43, v8
	v_mov_b32_e32 v44, v8
	v_mov_b32_e32 v45, v8
	v_mov_b32_e32 v46, v8
	v_mov_b32_e32 v47, v8
	v_mov_b32_e32 v56, v8
	v_mov_b32_e32 v57, v8
	v_mov_b32_e32 v58, v8
	v_mov_b32_e32 v59, v8
	v_mov_b32_e32 v60, v8
	v_mov_b32_e32 v61, v8
	v_mov_b32_e32 v62, v8
	v_mov_b32_e32 v63, v8
	v_mov_b32_e32 v16, v8
	v_mov_b32_e32 v17, v8
	v_mov_b32_e32 v18, v8
	v_mov_b32_e32 v19, v8
	v_mov_b32_e32 v20, v8
	v_mov_b32_e32 v21, v8
	v_mov_b32_e32 v22, v8
	v_mov_b32_e32 v23, v8
	v_mov_b32_e32 v32, v8
	v_mov_b32_e32 v33, v8
	v_mov_b32_e32 v34, v8
	v_mov_b32_e32 v35, v8
	v_mov_b32_e32 v36, v8
	v_mov_b32_e32 v37, v8
	v_mov_b32_e32 v38, v8
	v_mov_b32_e32 v39, v8
	v_mov_b32_e32 v48, v8
	v_mov_b32_e32 v49, v8
	v_mov_b32_e32 v50, v8
	v_mov_b32_e32 v51, v8
	v_mov_b32_e32 v52, v8
	v_mov_b32_e32 v53, v8
	v_mov_b32_e32 v54, v8
	v_mov_b32_e32 v55, v8
	v_mov_b32_e32 v64, v8
	v_mov_b32_e32 v65, v8
	v_mov_b32_e32 v66, v8
	v_mov_b32_e32 v67, v8
	v_mov_b32_e32 v68, v8
	v_mov_b32_e32 v69, v8
	v_mov_b32_e32 v70, v8
	v_mov_b32_e32 v71, v8
	v_mov_b32_e32 v72, v8
	v_mov_b32_e32 v73, v8
	v_mov_b32_e32 v74, v8
	v_mov_b32_e32 v75, v8
	v_mov_b32_e32 v76, v8
	v_mov_b32_e32 v77, v8
	v_mov_b32_e32 v78, v8
	v_mov_b32_e32 v79, v8
	v_mov_b32_e32 v88, v8
	v_mov_b32_e32 v89, v8
	v_mov_b32_e32 v90, v8
	v_mov_b32_e32 v91, v8
	v_mov_b32_e32 v92, v8
	v_mov_b32_e32 v93, v8
	v_mov_b32_e32 v94, v8
	v_mov_b32_e32 v95, v8
	v_mov_b32_e32 v104, v8
	v_mov_b32_e32 v105, v8
	v_mov_b32_e32 v106, v8
	v_mov_b32_e32 v107, v8
	v_mov_b32_e32 v108, v8
	v_mov_b32_e32 v109, v8
	v_mov_b32_e32 v110, v8
	v_mov_b32_e32 v111, v8
	v_mov_b32_e32 v120, v8
	v_mov_b32_e32 v121, v8
	v_mov_b32_e32 v122, v8
	v_mov_b32_e32 v123, v8
	v_mov_b32_e32 v124, v8
	v_mov_b32_e32 v125, v8
	v_mov_b32_e32 v126, v8
	v_mov_b32_e32 v127, v8
	v_mov_b32_e32 v80, v8
	v_mov_b32_e32 v81, v8
	v_mov_b32_e32 v82, v8
	v_mov_b32_e32 v83, v8
	v_mov_b32_e32 v84, v8
	v_mov_b32_e32 v85, v8
	v_mov_b32_e32 v86, v8
	v_mov_b32_e32 v87, v8
	v_mov_b32_e32 v96, v8
	v_mov_b32_e32 v97, v8
	v_mov_b32_e32 v98, v8
	v_mov_b32_e32 v99, v8
	v_mov_b32_e32 v100, v8
	v_mov_b32_e32 v101, v8
	v_mov_b32_e32 v102, v8
	v_mov_b32_e32 v103, v8
	v_mov_b32_e32 v112, v8
	v_mov_b32_e32 v113, v8
	v_mov_b32_e32 v114, v8
	v_mov_b32_e32 v115, v8
	v_mov_b32_e32 v116, v8
	v_mov_b32_e32 v117, v8
	v_mov_b32_e32 v118, v8
	v_mov_b32_e32 v119, v8
	v_mov_b32_e32 v128, v8
	v_mov_b32_e32 v129, v8
	v_mov_b32_e32 v130, v8
	v_mov_b32_e32 v131, v8
	v_mov_b32_e32 v132, v8
	v_mov_b32_e32 v133, v8
	v_mov_b32_e32 v134, v8
	v_mov_b32_e32 v135, v8
	.p2align	6
